# barrier-nonleader-early-L1-invalidate
# speedup vs baseline: 1.0203x; 1.0052x over previous
.LBB0_597:
	s_or_b64 exec, exec, s[30:31]
	v_cvt_f32_u32_e32 v4, v2
	s_waitcnt vmcnt(0)
	v_readfirstlane_b32 s2, v3
	v_sub_u32_e32 v3, 0, v2
	v_rcp_iflag_f32_e32 v4, v4
	v_add_u32_e32 v5, s2, v1
	v_mul_f32_e32 v4, 0x4f7ffffe, v4
	v_cvt_u32_f32_e32 v4, v4
	v_mul_lo_u32 v1, v3, v4
	v_mul_hi_u32 v1, v4, v1
	v_add_u32_e32 v1, v4, v1
	v_mul_hi_u32 v1, v5, v1
	v_mul_lo_u32 v3, v1, v2
	v_sub_u32_e32 v3, v5, v3
	v_add_u32_e32 v4, 1, v1
	v_cmp_ge_u32_e32 vcc, v3, v2
	s_nop 1
	v_cndmask_b32_e32 v1, v1, v4, vcc
	v_sub_u32_e32 v4, v3, v2
	v_cndmask_b32_e32 v3, v3, v4, vcc
	v_add_u32_e32 v4, 1, v1
	v_cmp_ge_u32_e32 vcc, v3, v2
	v_add_u32_e32 v3, 1, v5
	s_nop 0
	v_cndmask_b32_e32 v1, v1, v4, vcc
	v_mul_lo_u32 v4, v2, v1
	v_add_u32_e32 v2, v4, v2
	v_cmp_ne_u32_e32 vcc, v3, v2
	s_and_saveexec_b64 s[4:5], vcc
	s_xor_b64 s[30:31], exec, s[4:5]
	s_cbranch_execz .LBB0_611
	buffer_inv sc1
	v_readlane_b32 s4, v253, 39
	v_readlane_b32 s5, v253, 40
	s_waitcnt lgkmcnt(0)
	s_nop 3
	global_load_dword v0, v97, s[4:5] sc1
	s_waitcnt vmcnt(0)
	v_cmp_eq_u32_e32 vcc, v0, v1
	s_and_saveexec_b64 s[36:37], vcc
	s_cbranch_execz .LBB0_610
	s_mov_b32 s2, 1
	s_mov_b64 s[38:39], 0
	s_branch .LBB0_601

.LBB0_610:
	s_or_b64 exec, exec, s[36:37]
	s_waitcnt vmcnt(0)
	s_waitcnt vmcnt(0)
